# hgrn_load prefix-sum phase 1: hoist the 8 LDS reads ahead of the running-sum chain (both copies)
# baseline (speedup 1.0000x reference)
; DI float bflo(unsigned w) { return __uint_as_float(w << 16); }
; DI float bfhi(unsigned w) { return __uint_as_float(w & 0xffff0000u); }
; DI float lg2(float x) { return __builtin_amdgcn_logf(x); }
; DI float log2_sigmoid(float z) { const float a = fabsf(z) * L2E; return -(fmaxf(-z, 0.f) * L2E + lg2(1.f + ex2(-a))); }
; DI float sigmoidf_(float z) { return 1.f / (1.f + ex2(-z * L2E)); }
; template <bool WANT_Q>
; DI void hgrn_load(const Params& p, int l, int bh, int c, float* QS, float* B2, float* LK, float* V, float* lbv) {
;     ...
;         const float lb = lbv[d];
;         float lf2;
;         if (lb == 0.f) lf2 = log2_sigmoid(z); else lf2 = lg2(lb + (1.f - lb) * sigmoidf_(z));
;         const float lk2 = lg2(1.f - lb) + log2_sigmoid(-z);
;         B2[t * HP + d] = lf2; LK[t * HP + d] = lk2;
;       }
;     }
;     const u32x4 v0 = *(const u32x4*)(prow + C_HI), v1 = *(const u32x4*)(prow + C_HI + 8);
;     const unsigned vw[8] = {v0.x, v0.y, v0.z, v0.w, v1.x, v1.y, v1.z, v1.w};
; #pragma unroll
;     for (int j = 0; j < 8; ++j) { V[t * HP + d0 + 2 * j] = bflo(vw[j]); V[t * HP + d0 + 2 * j + 1] = bfhi(vw[j]); }
;     if (WANT_Q) {
;       const u32x4 q0 = *(const u32x4*)(prow + C_HQ), q1 = *(const u32x4*)(prow + C_HQ + 8);
;       const unsigned qw[8] = {q0.x, q0.y, q0.z, q0.w, q1.x, q1.y, q1.z, q1.w};
; #pragma unroll
;       for (int j = 0; j < 8; ++j) { const float a = bflo(qw[j]), bq = bfhi(qw[j]); QS[t * HP + d0 + 2 * j] = a * sigmoidf_(a); QS[t * HP + d0 + 2 * j + 1] = bq * sigmoidf_(bq); }
.LBB0_611:
	s_andn2_saveexec_b64 s[2:3], s[2:3]
	v_add_f32_e32 v4, 1.0, v4
	v_log_f32_e32 v7, v4
	v_max_f32_e64 v4, -v2, -v2
	v_max_f32_e32 v4, 0, v4
	v_fmamk_f32 v4, v4, 0x3fb8aa3b, v7
	v_xor_b32_e32 v5, 0x80000000, v4
	s_or_b64 exec, exec, s[2:3]
	v_log_f32_e32 v3, v3
	v_max_f32_e32 v2, v2, v2
	v_max_f32_e32 v2, 0, v2
	v_fmac_f32_e32 v7, 0x3fb8aa3b, v2
	v_sub_f32_e32 v2, v3, v7
	v_add_u32_e32 v3, 60, v12
	ds_write2st64_b32 v3, v5, v2 offset0:68 offset1:136
	global_load_dwordx4 v[2:5], v[10:11], off offset:2320
	global_load_dwordx4 v[6:9], v[10:11], off offset:2304
	v_mov_b32_e32 v15, 0
	s_waitcnt vmcnt(0)
	v_lshlrev_b32_e32 v16, 16, v6
	v_and_b32_e32 v17, 0xffff0000, v6
	v_lshlrev_b32_e32 v18, 16, v7
	v_and_b32_e32 v19, 0xffff0000, v7
	v_lshlrev_b32_e32 v6, 16, v8
	v_and_b32_e32 v7, 0xffff0000, v8
	v_lshlrev_b32_e32 v8, 16, v9
	v_and_b32_e32 v9, 0xffff0000, v9
	ds_write_b128 v12, v[6:9] offset:52240
	v_lshlrev_b32_e32 v6, 16, v2
	v_and_b32_e32 v7, 0xffff0000, v2
	v_lshlrev_b32_e32 v8, 16, v3
	v_and_b32_e32 v9, 0xffff0000, v3
	v_lshlrev_b32_e32 v2, 16, v4
	v_and_b32_e32 v3, 0xffff0000, v4
	v_lshlrev_b32_e32 v4, 16, v5
	v_and_b32_e32 v5, 0xffff0000, v5
	ds_write_b128 v12, v[16:19] offset:52224
	ds_write_b128 v12, v[6:9] offset:52256
	ds_write_b128 v12, v[2:5] offset:52272
	global_load_dwordx4 v[2:5], v[10:11], off offset:1296
	global_load_dwordx4 v[6:9], v[10:11], off offset:1280
	s_waitcnt vmcnt(0)
	v_lshlrev_b32_e32 v10, 16, v6
	v_and_b32_e32 v11, 0xffff0000, v6
	v_mul_f32_e32 v6, 0xbfb8aa3b, v10
	v_exp_f32_e32 v16, v6
	v_mul_f32_e32 v6, 0xbfb8aa3b, v11
	v_exp_f32_e32 v17, v6
	s_nop 0
	v_pk_add_f32 v[16:17], v[16:17], 1.0 op_sel_hi:[1,0]
	s_nop 0
	v_div_scale_f32 v6, s[2:3], v17, v17, 1.0
	v_rcp_f32_e32 v18, v6
	s_nop 0
	v_fma_f32 v19, -v6, v18, 1.0
	v_fmac_f32_e32 v18, v19, v18
	v_div_scale_f32 v19, vcc, 1.0, v17, 1.0
	v_mul_f32_e32 v20, v19, v18
	v_fma_f32 v21, -v6, v20, v19
	v_fmac_f32_e32 v20, v21, v18
	v_fma_f32 v6, -v6, v20, v19
	v_div_fmas_f32 v6, v6, v18, v20
	v_div_fixup_f32 v17, v6, v17, 1.0
	v_div_scale_f32 v6, s[2:3], v16, v16, 1.0
	v_rcp_f32_e32 v18, v6
	s_nop 0
	v_fma_f32 v19, -v6, v18, 1.0
	v_fmac_f32_e32 v18, v19, v18
	v_div_scale_f32 v19, vcc, 1.0, v16, 1.0
	v_mul_f32_e32 v20, v19, v18
	v_fma_f32 v21, -v6, v20, v19
	v_fmac_f32_e32 v20, v21, v18
	v_fma_f32 v6, -v6, v20, v19
	v_div_fmas_f32 v6, v6, v18, v20
	v_div_fixup_f32 v16, v6, v16, 1.0
	v_lshlrev_b32_e32 v6, 16, v7
	v_and_b32_e32 v7, 0xffff0000, v7
	v_pk_mul_f32 v[16:17], v[16:17], v[10:11]
	v_mul_f32_e32 v10, 0xbfb8aa3b, v6
	v_mul_f32_e32 v11, 0xbfb8aa3b, v7
	v_exp_f32_e32 v10, v10
	v_exp_f32_e32 v11, v11
	s_nop 0
	v_pk_add_f32 v[10:11], v[10:11], 1.0 op_sel_hi:[1,0]
	s_nop 0
	v_div_scale_f32 v18, s[2:3], v11, v11, 1.0
	v_rcp_f32_e32 v19, v18
	s_nop 0
	v_fma_f32 v20, -v18, v19, 1.0
	v_fmac_f32_e32 v19, v20, v19
	v_div_scale_f32 v20, vcc, 1.0, v11, 1.0
	v_mul_f32_e32 v21, v20, v19
	v_fma_f32 v22, -v18, v21, v20
	v_fmac_f32_e32 v21, v22, v19
	v_fma_f32 v18, -v18, v21, v20
	v_div_fmas_f32 v18, v18, v19, v21
	v_div_fixup_f32 v11, v18, v11, 1.0
	v_div_scale_f32 v18, s[2:3], v10, v10, 1.0
	v_rcp_f32_e32 v19, v18
	s_nop 0
	v_fma_f32 v20, -v18, v19, 1.0
	v_fmac_f32_e32 v19, v20, v19
	v_div_scale_f32 v20, vcc, 1.0, v10, 1.0
	v_mul_f32_e32 v21, v20, v19
	v_fma_f32 v22, -v18, v21, v20
	v_fmac_f32_e32 v21, v22, v19
	v_fma_f32 v18, -v18, v21, v20
	v_div_fmas_f32 v18, v18, v19, v21
	v_div_fixup_f32 v10, v18, v10, 1.0
	v_pk_mul_f32 v[18:19], v[10:11], v[6:7]
	v_lshlrev_b32_e32 v6, 16, v8
	v_and_b32_e32 v7, 0xffff0000, v8
	v_mul_f32_e32 v8, 0xbfb8aa3b, v6
	v_exp_f32_e32 v10, v8
	v_mul_f32_e32 v8, 0xbfb8aa3b, v7
	v_exp_f32_e32 v11, v8
	ds_write_b128 v12, v[16:19]
	v_pk_add_f32 v[10:11], v[10:11], 1.0 op_sel_hi:[1,0]
	s_nop 0
	v_div_scale_f32 v8, s[2:3], v11, v11, 1.0
	v_rcp_f32_e32 v16, v8
	s_nop 0
	v_fma_f32 v17, -v8, v16, 1.0
	v_fmac_f32_e32 v16, v17, v16
	v_div_scale_f32 v17, vcc, 1.0, v11, 1.0
	v_mul_f32_e32 v18, v17, v16
	v_fma_f32 v19, -v8, v18, v17
	v_fmac_f32_e32 v18, v19, v16
	v_fma_f32 v8, -v8, v18, v17
	v_div_fmas_f32 v8, v8, v16, v18
	v_div_fixup_f32 v11, v8, v11, 1.0
	v_div_scale_f32 v8, s[2:3], v10, v10, 1.0
	v_rcp_f32_e32 v16, v8
	s_nop 0
	v_fma_f32 v17, -v8, v16, 1.0
	v_fmac_f32_e32 v16, v17, v16
	v_div_scale_f32 v17, vcc, 1.0, v10, 1.0
	v_mul_f32_e32 v18, v17, v16
	v_fma_f32 v19, -v8, v18, v17
	v_fmac_f32_e32 v18, v19, v16
	v_fma_f32 v8, -v8, v18, v17
	v_div_fmas_f32 v8, v8, v16, v18
	v_div_fixup_f32 v10, v8, v10, 1.0
	v_lshlrev_b32_e32 v8, 16, v9
	v_and_b32_e32 v9, 0xffff0000, v9
	v_pk_mul_f32 v[6:7], v[10:11], v[6:7]
	v_mul_f32_e32 v10, 0xbfb8aa3b, v8
	v_mul_f32_e32 v11, 0xbfb8aa3b, v9
	v_exp_f32_e32 v10, v10
	v_exp_f32_e32 v11, v11
	s_nop 0
	v_pk_add_f32 v[10:11], v[10:11], 1.0 op_sel_hi:[1,0]
	s_nop 0
	v_div_scale_f32 v16, s[2:3], v11, v11, 1.0
	v_rcp_f32_e32 v17, v16
	s_nop 0
	v_fma_f32 v18, -v16, v17, 1.0
	v_fmac_f32_e32 v17, v18, v17
	v_div_scale_f32 v18, vcc, 1.0, v11, 1.0
	v_mul_f32_e32 v19, v18, v17
	v_fma_f32 v20, -v16, v19, v18
	v_fmac_f32_e32 v19, v20, v17
	v_fma_f32 v16, -v16, v19, v18
	v_div_fmas_f32 v16, v16, v17, v19
	v_div_fixup_f32 v11, v16, v11, 1.0
	v_div_scale_f32 v16, s[2:3], v10, v10, 1.0
	v_rcp_f32_e32 v17, v16
	s_nop 0
	v_fma_f32 v18, -v16, v17, 1.0
	v_fmac_f32_e32 v17, v18, v17
	v_div_scale_f32 v18, vcc, 1.0, v10, 1.0
	v_mul_f32_e32 v19, v18, v17
	v_fma_f32 v20, -v16, v19, v18
	v_fmac_f32_e32 v19, v20, v17
	v_fma_f32 v16, -v16, v19, v18
	v_div_fmas_f32 v16, v16, v17, v19
	v_div_fixup_f32 v10, v16, v10, 1.0
	v_pk_mul_f32 v[8:9], v[10:11], v[8:9]
	ds_write_b128 v12, v[6:9] offset:16
	v_lshlrev_b32_e32 v6, 16, v2
	v_and_b32_e32 v7, 0xffff0000, v2
; DI float bflo(unsigned w) { return __uint_as_float(w << 16); }
; DI float bfhi(unsigned w) { return __uint_as_float(w & 0xffff0000u); }
; DI float sigmoidf_(float z) { return 1.f / (1.f + ex2(-z * L2E)); }
; template <bool WANT_Q>
; DI void hgrn_load(const Params& p, int l, int bh, int c, float* QS, float* B2, float* LK, float* V, float* lbv) {
;     ...
;       for (int j = 0; j < 8; ++j) { const float a = bflo(qw[j]), bq = bfhi(qw[j]); QS[t * HP + d0 + 2 * j] = a * sigmoidf_(a); QS[t * HP + d0 + 2 * j + 1] = bq * sigmoidf_(bq); }
;     }
;   }
;   __syncthreads();
;   {
;     const int d = tid & 63, seg = tid >> 6;
;     float run = 0.f;
; #pragma unroll
;     for (int i = 0; i < 16; ++i) { const int tt = seg * 16 + i; run += B2[tt * HP + d]; B2[tt * HP + d] = run; }
	v_mul_f32_e32 v2, 0xbfb8aa3b, v6
	v_exp_f32_e32 v8, v2
	v_mul_f32_e32 v2, 0xbfb8aa3b, v7
	v_exp_f32_e32 v9, v2
	s_nop 0
	v_pk_add_f32 v[8:9], v[8:9], 1.0 op_sel_hi:[1,0]
	s_nop 0
	v_div_scale_f32 v2, s[2:3], v9, v9, 1.0
	v_rcp_f32_e32 v10, v2
	s_nop 0
	v_fma_f32 v11, -v2, v10, 1.0
	v_fmac_f32_e32 v10, v11, v10
	v_div_scale_f32 v11, vcc, 1.0, v9, 1.0
	v_mul_f32_e32 v16, v11, v10
	v_fma_f32 v17, -v2, v16, v11
	v_fmac_f32_e32 v16, v17, v10
	v_fma_f32 v2, -v2, v16, v11
	v_div_fmas_f32 v2, v2, v10, v16
	v_div_fixup_f32 v9, v2, v9, 1.0
	v_div_scale_f32 v2, s[2:3], v8, v8, 1.0
	v_rcp_f32_e32 v10, v2
	s_nop 0
	v_fma_f32 v11, -v2, v10, 1.0
	v_fmac_f32_e32 v10, v11, v10
	v_div_scale_f32 v11, vcc, 1.0, v8, 1.0
	v_mul_f32_e32 v16, v11, v10
	v_fma_f32 v17, -v2, v16, v11
	v_fmac_f32_e32 v16, v17, v10
	v_fma_f32 v2, -v2, v16, v11
	v_div_fmas_f32 v2, v2, v10, v16
	v_div_fixup_f32 v8, v2, v8, 1.0
	v_lshlrev_b32_e32 v2, 16, v3
	v_and_b32_e32 v3, 0xffff0000, v3
	v_pk_mul_f32 v[6:7], v[8:9], v[6:7]
	v_mul_f32_e32 v8, 0xbfb8aa3b, v2
	v_mul_f32_e32 v9, 0xbfb8aa3b, v3
	v_exp_f32_e32 v8, v8
	v_exp_f32_e32 v9, v9
	s_nop 0
	v_pk_add_f32 v[8:9], v[8:9], 1.0 op_sel_hi:[1,0]
	s_nop 0
	v_div_scale_f32 v10, s[2:3], v9, v9, 1.0
	v_rcp_f32_e32 v11, v10
	s_nop 0
	v_fma_f32 v16, -v10, v11, 1.0
	v_fmac_f32_e32 v11, v16, v11
	v_div_scale_f32 v16, vcc, 1.0, v9, 1.0
	v_mul_f32_e32 v17, v16, v11
	v_fma_f32 v18, -v10, v17, v16
	v_fmac_f32_e32 v17, v18, v11
	v_fma_f32 v10, -v10, v17, v16
	v_div_fmas_f32 v10, v10, v11, v17
	v_div_fixup_f32 v9, v10, v9, 1.0
	v_div_scale_f32 v10, s[2:3], v8, v8, 1.0
	v_rcp_f32_e32 v11, v10
	s_nop 0
	v_fma_f32 v16, -v10, v11, 1.0
	v_fmac_f32_e32 v11, v16, v11
	v_div_scale_f32 v16, vcc, 1.0, v8, 1.0
	v_mul_f32_e32 v17, v16, v11
	v_fma_f32 v18, -v10, v17, v16
	v_fmac_f32_e32 v17, v18, v11
	v_fma_f32 v10, -v10, v17, v16
	v_div_fmas_f32 v10, v10, v11, v17
	v_div_fixup_f32 v8, v10, v8, 1.0
	v_pk_mul_f32 v[8:9], v[8:9], v[2:3]
	v_lshlrev_b32_e32 v2, 16, v4
	v_and_b32_e32 v3, 0xffff0000, v4
	v_mul_f32_e32 v4, 0xbfb8aa3b, v2
	ds_write_b128 v12, v[6:9] offset:32
	v_exp_f32_e32 v6, v4
	v_mul_f32_e32 v4, 0xbfb8aa3b, v3
	v_exp_f32_e32 v7, v4
	s_nop 0
	v_pk_add_f32 v[6:7], v[6:7], 1.0 op_sel_hi:[1,0]
	s_nop 0
	v_div_scale_f32 v4, s[2:3], v7, v7, 1.0
	v_rcp_f32_e32 v8, v4
	s_nop 0
	v_fma_f32 v9, -v4, v8, 1.0
	v_fmac_f32_e32 v8, v9, v8
	v_div_scale_f32 v9, vcc, 1.0, v7, 1.0
	v_mul_f32_e32 v10, v9, v8
	v_fma_f32 v11, -v4, v10, v9
	v_fmac_f32_e32 v10, v11, v8
	v_fma_f32 v4, -v4, v10, v9
	v_div_fmas_f32 v4, v4, v8, v10
	v_div_fixup_f32 v7, v4, v7, 1.0
	v_div_scale_f32 v4, s[2:3], v6, v6, 1.0
	v_rcp_f32_e32 v8, v4
	s_nop 0
	v_fma_f32 v9, -v4, v8, 1.0
	v_fmac_f32_e32 v8, v9, v8
	v_div_scale_f32 v9, vcc, 1.0, v6, 1.0
	v_mul_f32_e32 v10, v9, v8
	v_fma_f32 v11, -v4, v10, v9
	v_fmac_f32_e32 v10, v11, v8
	v_fma_f32 v4, -v4, v10, v9
	v_div_fmas_f32 v4, v4, v8, v10
	v_div_fixup_f32 v6, v4, v6, 1.0
	v_lshlrev_b32_e32 v4, 16, v5
	v_and_b32_e32 v5, 0xffff0000, v5
	v_pk_mul_f32 v[2:3], v[6:7], v[2:3]
	v_mul_f32_e32 v6, 0xbfb8aa3b, v4
	v_mul_f32_e32 v7, 0xbfb8aa3b, v5
	v_exp_f32_e32 v6, v6
	v_exp_f32_e32 v7, v7
	s_nop 0
	v_pk_add_f32 v[6:7], v[6:7], 1.0 op_sel_hi:[1,0]
	s_nop 0
	v_div_scale_f32 v8, s[2:3], v7, v7, 1.0
	v_rcp_f32_e32 v9, v8
	s_nop 0
	v_fma_f32 v10, -v8, v9, 1.0
	v_fmac_f32_e32 v9, v10, v9
	v_div_scale_f32 v10, vcc, 1.0, v7, 1.0
	v_mul_f32_e32 v11, v10, v9
	v_fma_f32 v16, -v8, v11, v10
	v_fmac_f32_e32 v11, v16, v9
	v_fma_f32 v8, -v8, v11, v10
	v_div_fmas_f32 v8, v8, v9, v11
	v_div_fixup_f32 v7, v8, v7, 1.0
	v_div_scale_f32 v8, s[2:3], v6, v6, 1.0
	v_rcp_f32_e32 v9, v8
	s_nop 0
	v_fma_f32 v10, -v8, v9, 1.0
	v_fmac_f32_e32 v9, v10, v9
	v_div_scale_f32 v10, vcc, 1.0, v6, 1.0
	v_mul_f32_e32 v11, v10, v9
	v_fma_f32 v16, -v8, v11, v10
	v_fmac_f32_e32 v11, v16, v9
	v_fma_f32 v8, -v8, v11, v10
	v_div_fmas_f32 v8, v8, v9, v11
	v_div_fixup_f32 v6, v8, v6, 1.0
	v_pk_mul_f32 v[4:5], v[6:7], v[4:5]
	v_and_b32_e32 v7, 63, v13
	v_lshrrev_b32_e32 v6, 6, v14
	ds_write_b128 v12, v[2:5] offset:48
	v_mul_u32_u24_e32 v2, 0x1100, v6
	v_lshlrev_b32_e32 v3, 2, v7
	v_add3_u32 v10, v250, v2, v3
	v_add_u32_e32 v5, 0x4400, v10
	s_waitcnt lgkmcnt(0)
	s_barrier
	ds_read2_b32 v[140:141], v5 offset1:68
	ds_read2_b32 v[142:143], v5 offset0:136 offset1:204
	v_add_u32_e32 v4, 0x4800, v10
	v_add_u32_e32 v3, 0x4c00, v10
	v_add_u32_e32 v2, 0x5000, v10
	ds_read2_b32 v[144:145], v4 offset0:16 offset1:84
	ds_read2_b32 v[146:147], v4 offset0:152 offset1:220
	ds_read2_b32 v[148:149], v3 offset0:32 offset1:100
	ds_read2_b32 v[150:151], v3 offset0:168 offset1:236
	ds_read2_b32 v[152:153], v2 offset0:48 offset1:116
	ds_read2_b32 v[154:155], v2 offset0:184 offset1:252
	s_waitcnt lgkmcnt(0)
	v_add_f32_e32 v140, 0, v140
	v_add_f32_e32 v141, v140, v141
	ds_write2_b32 v5, v140, v141 offset1:68
	v_add_f32_e32 v142, v141, v142
	v_add_f32_e32 v143, v142, v143
	ds_write2_b32 v5, v142, v143 offset0:136 offset1:204
	v_add_f32_e32 v144, v143, v144
	v_add_f32_e32 v145, v144, v145
	ds_write2_b32 v4, v144, v145 offset0:16 offset1:84
	v_add_f32_e32 v146, v145, v146
	v_add_f32_e32 v147, v146, v147
	ds_write2_b32 v4, v146, v147 offset0:152 offset1:220
	v_add_f32_e32 v148, v147, v148
	v_add_f32_e32 v149, v148, v149
	ds_write2_b32 v3, v148, v149 offset0:32 offset1:100
	v_add_f32_e32 v150, v149, v150
	v_add_f32_e32 v151, v150, v151
	ds_write2_b32 v3, v150, v151 offset0:168 offset1:236
	v_add_f32_e32 v152, v151, v152
	v_add_f32_e32 v153, v152, v153
	ds_write2_b32 v2, v152, v153 offset0:48 offset1:116
	v_add_f32_e32 v154, v153, v154
	v_add_f32_e32 v155, v154, v155
	ds_write2_b32 v2, v154, v155 offset0:184 offset1:252
	s_waitcnt lgkmcnt(0)
	s_barrier
	s_and_saveexec_b64 s[2:3], s[0:1]
	s_cbranch_execz .LBB0_617
	v_lshl_add_u32 v7, v7, 2, v45
	v_mov_b32_e32 v15, 0
	s_mov_b64 s[0:1], 0

; DI float bflo(unsigned w) { return __uint_as_float(w << 16); }
; DI float bfhi(unsigned w) { return __uint_as_float(w & 0xffff0000u); }
; DI float lg2(float x) { return __builtin_amdgcn_logf(x); }
; DI float log2_sigmoid(float z) { const float a = fabsf(z) * L2E; return -(fmaxf(-z, 0.f) * L2E + lg2(1.f + ex2(-a))); }
; DI float sigmoidf_(float z) { return 1.f / (1.f + ex2(-z * L2E)); }
; template <bool WANT_Q>
; DI void hgrn_load(const Params& p, int l, int bh, int c, float* QS, float* B2, float* LK, float* V, float* lbv) {
;     ...
;         const float lb = lbv[d];
;         float lf2;
;         if (lb == 0.f) lf2 = log2_sigmoid(z); else lf2 = lg2(lb + (1.f - lb) * sigmoidf_(z));
;         const float lk2 = lg2(1.f - lb) + log2_sigmoid(-z);
;         B2[t * HP + d] = lf2; LK[t * HP + d] = lk2;
;       }
;     }
;     const u32x4 v0 = *(const u32x4*)(prow + C_HI), v1 = *(const u32x4*)(prow + C_HI + 8);
;     const unsigned vw[8] = {v0.x, v0.y, v0.z, v0.w, v1.x, v1.y, v1.z, v1.w};
; #pragma unroll
;     for (int j = 0; j < 8; ++j) { V[t * HP + d0 + 2 * j] = bflo(vw[j]); V[t * HP + d0 + 2 * j + 1] = bfhi(vw[j]); }
;     if (WANT_Q) {
;       const u32x4 q0 = *(const u32x4*)(prow + C_HQ), q1 = *(const u32x4*)(prow + C_HQ + 8);
;       const unsigned qw[8] = {q0.x, q0.y, q0.z, q0.w, q1.x, q1.y, q1.z, q1.w};
; #pragma unroll
;       for (int j = 0; j < 8; ++j) { const float a = bflo(qw[j]), bq = bfhi(qw[j]); QS[t * HP + d0 + 2 * j] = a * sigmoidf_(a); QS[t * HP + d0 + 2 * j + 1] = bq * sigmoidf_(bq); }
;     }
;   }
;   __syncthreads();
;   {
;     const int d = tid & 63, seg = tid >> 6;
;     float run = 0.f;
; #pragma unroll
;     for (int i = 0; i < 16; ++i) { const int tt = seg * 16 + i; run += B2[tt * HP + d]; B2[tt * HP + d] = run; }
.LBB0_819:
	s_andn2_saveexec_b64 s[2:3], s[2:3]
	v_add_f32_e32 v4, 1.0, v4
	v_log_f32_e32 v7, v4
	v_max_f32_e64 v4, -v2, -v2
	v_max_f32_e32 v4, 0, v4
	v_fmamk_f32 v4, v4, 0x3fb8aa3b, v7
	v_xor_b32_e32 v5, 0x80000000, v4
	s_or_b64 exec, exec, s[2:3]
	v_log_f32_e32 v3, v3
	v_max_f32_e32 v4, v2, v2
	v_max_f32_e32 v4, 0, v4
	v_fmac_f32_e32 v7, 0x3fb8aa3b, v4
	v_sub_f32_e32 v3, v3, v7
	v_add_u32_e32 v4, 60, v0
	ds_write2st64_b32 v4, v5, v3 offset0:68 offset1:136
	global_load_dwordx4 v[4:7], v[10:11], off offset:2320
	s_nop 0
	global_load_dwordx4 v[8:11], v[10:11], off offset:2304
	v_mov_b32_e32 v2, 0
	s_waitcnt vmcnt(0)
	v_lshlrev_b32_e32 v14, 16, v8
	v_and_b32_e32 v15, 0xffff0000, v8
	v_lshlrev_b32_e32 v16, 16, v9
	v_and_b32_e32 v17, 0xffff0000, v9
	v_lshlrev_b32_e32 v8, 16, v10
	v_and_b32_e32 v9, 0xffff0000, v10
	v_lshlrev_b32_e32 v10, 16, v11
	v_and_b32_e32 v11, 0xffff0000, v11
	ds_write_b128 v0, v[8:11] offset:52240
	v_lshlrev_b32_e32 v8, 16, v4
	v_and_b32_e32 v9, 0xffff0000, v4
	v_lshlrev_b32_e32 v10, 16, v5
	v_and_b32_e32 v11, 0xffff0000, v5
	v_lshlrev_b32_e32 v4, 16, v6
	v_and_b32_e32 v5, 0xffff0000, v6
	v_lshlrev_b32_e32 v6, 16, v7
	v_and_b32_e32 v7, 0xffff0000, v7
	ds_write_b128 v0, v[8:11] offset:52256
	ds_write_b128 v0, v[4:7] offset:52272
	v_and_b32_e32 v8, 63, v12
	v_lshrrev_b32_e32 v7, 6, v13
	v_mul_u32_u24_e32 v3, 0x1100, v7
	v_lshlrev_b32_e32 v4, 2, v8
	v_add3_u32 v3, v250, v3, v4
	v_add_u32_e32 v6, 0x4400, v3
	ds_write_b128 v0, v[14:17] offset:52224
	s_waitcnt lgkmcnt(0)
	s_barrier
	ds_read2_b32 v[64:65], v6 offset1:68
	ds_read2_b32 v[66:67], v6 offset0:136 offset1:204
	v_add_u32_e32 v5, 0x4800, v3
	v_add_u32_e32 v4, 0x4c00, v3
	v_add_u32_e32 v3, 0x5000, v3
	ds_read2_b32 v[68:69], v5 offset0:16 offset1:84
	ds_read2_b32 v[70:71], v5 offset0:152 offset1:220
	ds_read2_b32 v[72:73], v4 offset0:32 offset1:100
	ds_read2_b32 v[74:75], v4 offset0:168 offset1:236
	ds_read2_b32 v[76:77], v3 offset0:48 offset1:116
	ds_read2_b32 v[78:79], v3 offset0:184 offset1:252
	s_waitcnt lgkmcnt(0)
	v_add_f32_e32 v64, 0, v64
	v_add_f32_e32 v65, v64, v65
	ds_write2_b32 v6, v64, v65 offset1:68
	v_add_f32_e32 v66, v65, v66
	v_add_f32_e32 v67, v66, v67
	ds_write2_b32 v6, v66, v67 offset0:136 offset1:204
	v_add_f32_e32 v68, v67, v68
	v_add_f32_e32 v69, v68, v69
	ds_write2_b32 v5, v68, v69 offset0:16 offset1:84
	v_add_f32_e32 v70, v69, v70
	v_add_f32_e32 v71, v70, v71
	ds_write2_b32 v5, v70, v71 offset0:152 offset1:220
	v_add_f32_e32 v72, v71, v72
	v_add_f32_e32 v73, v72, v73
	ds_write2_b32 v4, v72, v73 offset0:32 offset1:100
	v_add_f32_e32 v74, v73, v74
	v_add_f32_e32 v75, v74, v75
	ds_write2_b32 v4, v74, v75 offset0:168 offset1:236
	v_add_f32_e32 v76, v75, v76
	v_add_f32_e32 v77, v76, v77
	ds_write2_b32 v3, v76, v77 offset0:48 offset1:116
	v_add_f32_e32 v78, v77, v78
	v_add_f32_e32 v79, v78, v79
	ds_write2_b32 v3, v78, v79 offset0:184 offset1:252
	s_waitcnt lgkmcnt(0)
	s_barrier
	s_and_saveexec_b64 s[2:3], s[40:41]
	s_cbranch_execz .LBB0_825
	v_lshl_add_u32 v8, v8, 2, v21
	v_mov_b32_e32 v2, 0
	s_mov_b64 s[4:5], 0
